# residual epilogue: nontemporal hint removed from the lo-half stores (cache policy experiment)
# speedup vs baseline: 1.0029x; 1.0003x over previous
; DI unsigned cvtpk(float lo, float hi) { f32x2_t v = {lo, hi}; bf16x2_t b = __builtin_convertvector(v, bf16x2_t); return __builtin_bit_cast(unsigned, b); }
; DI float bflo(unsigned w) { return __uint_as_float(w << 16); }
; DI float bfhi(unsigned w) { return __uint_as_float(w & 0xffff0000u); }
;     DI void operator()(const f32x4 (&acc)[2][2][4][2], const Unit& u, int wr, int wc, int fr, int fq) const {
;     ...
;                     if (loout) { u32x4 wl;
; #pragma unroll
;                         for (int j = 0; j < 4; ++j) wl[j] = cvtpk(o[2 * j] - bflo(w[j]), o[2 * j + 1] - bfhi(w[j]));
;                         __builtin_nontemporal_store(wl, (u32x4*)(loout + o2)); }
.LBB0_533:
	s_cmp_eq_u64 s[0:1], 0
	s_cbranch_scc1 .LBB0_535
	v_lshlrev_b32_e32 v206, 16, v194
	v_and_b32_e32 v207, 0xffff0000, v194
	v_pk_add_f32 v[206:207], v[186:187], v[206:207] neg_lo:[0,1] neg_hi:[0,1]
	s_nop 0
	v_cvt_pk_bf16_f32 v194, v206, v207
	v_lshlrev_b32_e32 v206, 16, v195
	v_and_b32_e32 v207, 0xffff0000, v195
	v_pk_add_f32 v[206:207], v[188:189], v[206:207] neg_lo:[0,1] neg_hi:[0,1]
	s_nop 0
	v_cvt_pk_bf16_f32 v195, v206, v207
	v_lshlrev_b32_e32 v206, 16, v196
	v_and_b32_e32 v207, 0xffff0000, v196
	v_pk_add_f32 v[206:207], v[190:191], v[206:207] neg_lo:[0,1] neg_hi:[0,1]
	s_nop 0
	v_cvt_pk_bf16_f32 v196, v206, v207
	v_lshlrev_b32_e32 v206, 16, v197
	v_and_b32_e32 v207, 0xffff0000, v197
	v_pk_add_f32 v[206:207], v[192:193], v[206:207] neg_lo:[0,1] neg_hi:[0,1]
	s_nop 0
	v_cvt_pk_bf16_f32 v197, v206, v207
	v_lshl_add_u64 v[206:207], v[220:221], 1, s[0:1]
	flat_store_dwordx4 v[206:207], v[194:197]

; DI unsigned cvtpk(float lo, float hi) { f32x2_t v = {lo, hi}; bf16x2_t b = __builtin_convertvector(v, bf16x2_t); return __builtin_bit_cast(unsigned, b); }
; DI float bflo(unsigned w) { return __uint_as_float(w << 16); }
; DI float bfhi(unsigned w) { return __uint_as_float(w & 0xffff0000u); }
;     DI void operator()(const f32x4 (&acc)[2][2][4][2], const Unit& u, int wr, int wc, int fr, int fq) const {
;     ...
;                     if (loout) { u32x4 wl;
; #pragma unroll
;                         for (int j = 0; j < 4; ++j) wl[j] = cvtpk(o[2 * j] - bflo(w[j]), o[2 * j + 1] - bfhi(w[j]));
;                         __builtin_nontemporal_store(wl, (u32x4*)(loout + o2)); }
.LBB0_541:
	s_cmp_eq_u64 s[0:1], 0
	s_cbranch_scc1 .LBB0_543
	v_lshlrev_b32_e32 v206, 16, v194
	v_and_b32_e32 v207, 0xffff0000, v194
	v_pk_add_f32 v[206:207], v[182:183], v[206:207] neg_lo:[0,1] neg_hi:[0,1]
	s_nop 0
	v_cvt_pk_bf16_f32 v194, v206, v207
	v_lshlrev_b32_e32 v206, 16, v195
	v_and_b32_e32 v207, 0xffff0000, v195
	v_pk_add_f32 v[206:207], v[184:185], v[206:207] neg_lo:[0,1] neg_hi:[0,1]
	s_nop 0
	v_cvt_pk_bf16_f32 v195, v206, v207
	v_lshlrev_b32_e32 v206, 16, v196
	v_and_b32_e32 v207, 0xffff0000, v196
	v_pk_add_f32 v[206:207], v[178:179], v[206:207] neg_lo:[0,1] neg_hi:[0,1]
	s_nop 0
	v_cvt_pk_bf16_f32 v196, v206, v207
	v_lshlrev_b32_e32 v206, 16, v197
	v_and_b32_e32 v207, 0xffff0000, v197
	v_pk_add_f32 v[206:207], v[180:181], v[206:207] neg_lo:[0,1] neg_hi:[0,1]
	s_nop 0
	v_cvt_pk_bf16_f32 v197, v206, v207
	v_lshl_add_u64 v[206:207], v[220:221], 1, s[0:1]
	flat_store_dwordx4 v[206:207], v[194:197] offset:256

; DI unsigned cvtpk(float lo, float hi) { f32x2_t v = {lo, hi}; bf16x2_t b = __builtin_convertvector(v, bf16x2_t); return __builtin_bit_cast(unsigned, b); }
; DI float bflo(unsigned w) { return __uint_as_float(w << 16); }
; DI float bfhi(unsigned w) { return __uint_as_float(w & 0xffff0000u); }
;     DI void operator()(const f32x4 (&acc)[2][2][4][2], const Unit& u, int wr, int wc, int fr, int fq) const {
;     ...
;                     if (loout) { u32x4 wl;
; #pragma unroll
;                         for (int j = 0; j < 4; ++j) wl[j] = cvtpk(o[2 * j] - bflo(w[j]), o[2 * j + 1] - bfhi(w[j]));
;                         __builtin_nontemporal_store(wl, (u32x4*)(loout + o2)); }
.LBB0_551:
	s_cmp_eq_u64 s[0:1], 0
	s_cbranch_scc1 .LBB0_553
	v_lshlrev_b32_e32 v186, 16, v178
	v_and_b32_e32 v187, 0xffff0000, v178
	v_pk_add_f32 v[186:187], v[174:175], v[186:187] neg_lo:[0,1] neg_hi:[0,1]
	s_nop 0
	v_cvt_pk_bf16_f32 v178, v186, v187
	v_lshlrev_b32_e32 v186, 16, v179
	v_and_b32_e32 v187, 0xffff0000, v179
	v_pk_add_f32 v[186:187], v[176:177], v[186:187] neg_lo:[0,1] neg_hi:[0,1]
	s_nop 0
	v_cvt_pk_bf16_f32 v179, v186, v187
	v_lshlrev_b32_e32 v186, 16, v180
	v_and_b32_e32 v187, 0xffff0000, v180
	v_pk_add_f32 v[186:187], v[170:171], v[186:187] neg_lo:[0,1] neg_hi:[0,1]
	s_nop 0
	v_cvt_pk_bf16_f32 v180, v186, v187
	v_lshlrev_b32_e32 v186, 16, v181
	v_and_b32_e32 v187, 0xffff0000, v181
	v_pk_add_f32 v[186:187], v[172:173], v[186:187] neg_lo:[0,1] neg_hi:[0,1]
	s_nop 0
	v_cvt_pk_bf16_f32 v181, v186, v187
	v_lshl_add_u64 v[186:187], v[184:185], 1, s[0:1]
	flat_store_dwordx4 v[186:187], v[178:181]

; DI unsigned cvtpk(float lo, float hi) { f32x2_t v = {lo, hi}; bf16x2_t b = __builtin_convertvector(v, bf16x2_t); return __builtin_bit_cast(unsigned, b); }
; DI float bflo(unsigned w) { return __uint_as_float(w << 16); }
; DI float bfhi(unsigned w) { return __uint_as_float(w & 0xffff0000u); }
;     DI void operator()(const f32x4 (&acc)[2][2][4][2], const Unit& u, int wr, int wc, int fr, int fq) const {
;     ...
;                     if (loout) { u32x4 wl;
; #pragma unroll
;                         for (int j = 0; j < 4; ++j) wl[j] = cvtpk(o[2 * j] - bflo(w[j]), o[2 * j + 1] - bfhi(w[j]));
;                         __builtin_nontemporal_store(wl, (u32x4*)(loout + o2)); }
.LBB0_559:
	s_cmp_eq_u64 s[0:1], 0
	s_cbranch_scc1 .LBB0_561
	v_lshlrev_b32_e32 v188, 16, v178
	v_and_b32_e32 v189, 0xffff0000, v178
	v_pk_add_f32 v[188:189], v[166:167], v[188:189] neg_lo:[0,1] neg_hi:[0,1]
	v_lshl_add_u64 v[184:185], v[184:185], 1, s[0:1]
	v_cvt_pk_bf16_f32 v178, v188, v189
	v_lshlrev_b32_e32 v188, 16, v179
	v_and_b32_e32 v189, 0xffff0000, v179
	v_pk_add_f32 v[188:189], v[168:169], v[188:189] neg_lo:[0,1] neg_hi:[0,1]
	s_nop 0
	v_cvt_pk_bf16_f32 v179, v188, v189
	v_lshlrev_b32_e32 v188, 16, v180
	v_and_b32_e32 v189, 0xffff0000, v180
	v_pk_add_f32 v[188:189], v[162:163], v[188:189] neg_lo:[0,1] neg_hi:[0,1]
	s_nop 0
	v_cvt_pk_bf16_f32 v180, v188, v189
	v_lshlrev_b32_e32 v188, 16, v181
	v_and_b32_e32 v189, 0xffff0000, v181
	v_pk_add_f32 v[188:189], v[164:165], v[188:189] neg_lo:[0,1] neg_hi:[0,1]
	s_nop 0
	v_cvt_pk_bf16_f32 v181, v188, v189
	flat_store_dwordx4 v[184:185], v[178:181] offset:256

; DI unsigned cvtpk(float lo, float hi) { f32x2_t v = {lo, hi}; bf16x2_t b = __builtin_convertvector(v, bf16x2_t); return __builtin_bit_cast(unsigned, b); }
; DI float bflo(unsigned w) { return __uint_as_float(w << 16); }
; DI float bfhi(unsigned w) { return __uint_as_float(w & 0xffff0000u); }
;     DI void operator()(const f32x4 (&acc)[2][2][4][2], const Unit& u, int wr, int wc, int fr, int fq) const {
;     ...
;                     if (loout) { u32x4 wl;
; #pragma unroll
;                         for (int j = 0; j < 4; ++j) wl[j] = cvtpk(o[2 * j] - bflo(w[j]), o[2 * j + 1] - bfhi(w[j]));
;                         __builtin_nontemporal_store(wl, (u32x4*)(loout + o2)); }
.LBB0_569:
	s_cmp_eq_u64 s[0:1], 0
	s_cbranch_scc1 .LBB0_571
	v_lshlrev_b32_e32 v170, 16, v162
	v_and_b32_e32 v171, 0xffff0000, v162
	v_pk_add_f32 v[170:171], v[158:159], v[170:171] neg_lo:[0,1] neg_hi:[0,1]
	s_nop 0
	v_cvt_pk_bf16_f32 v162, v170, v171
	v_lshlrev_b32_e32 v170, 16, v163
	v_and_b32_e32 v171, 0xffff0000, v163
	v_pk_add_f32 v[170:171], v[160:161], v[170:171] neg_lo:[0,1] neg_hi:[0,1]
	s_nop 0
	v_cvt_pk_bf16_f32 v163, v170, v171
	v_lshlrev_b32_e32 v170, 16, v164
	v_and_b32_e32 v171, 0xffff0000, v164
	v_pk_add_f32 v[170:171], v[154:155], v[170:171] neg_lo:[0,1] neg_hi:[0,1]
	s_nop 0
	v_cvt_pk_bf16_f32 v164, v170, v171
	v_lshlrev_b32_e32 v170, 16, v165
	v_and_b32_e32 v171, 0xffff0000, v165
	v_pk_add_f32 v[170:171], v[156:157], v[170:171] neg_lo:[0,1] neg_hi:[0,1]
	s_nop 0
	v_cvt_pk_bf16_f32 v165, v170, v171
	v_lshl_add_u64 v[170:171], v[168:169], 1, s[0:1]
	flat_store_dwordx4 v[170:171], v[162:165]

; DI unsigned cvtpk(float lo, float hi) { f32x2_t v = {lo, hi}; bf16x2_t b = __builtin_convertvector(v, bf16x2_t); return __builtin_bit_cast(unsigned, b); }
; DI float bflo(unsigned w) { return __uint_as_float(w << 16); }
; DI float bfhi(unsigned w) { return __uint_as_float(w & 0xffff0000u); }
;     DI void operator()(const f32x4 (&acc)[2][2][4][2], const Unit& u, int wr, int wc, int fr, int fq) const {
;     ...
;                     if (loout) { u32x4 wl;
; #pragma unroll
;                         for (int j = 0; j < 4; ++j) wl[j] = cvtpk(o[2 * j] - bflo(w[j]), o[2 * j + 1] - bfhi(w[j]));
;                         __builtin_nontemporal_store(wl, (u32x4*)(loout + o2)); }
.LBB0_577:
	s_cmp_eq_u64 s[0:1], 0
	s_cbranch_scc1 .LBB0_579
	v_lshlrev_b32_e32 v172, 16, v162
	v_and_b32_e32 v173, 0xffff0000, v162
	v_pk_add_f32 v[172:173], v[150:151], v[172:173] neg_lo:[0,1] neg_hi:[0,1]
	v_lshl_add_u64 v[168:169], v[168:169], 1, s[0:1]
	v_cvt_pk_bf16_f32 v162, v172, v173
	v_lshlrev_b32_e32 v172, 16, v163
	v_and_b32_e32 v173, 0xffff0000, v163
	v_pk_add_f32 v[172:173], v[152:153], v[172:173] neg_lo:[0,1] neg_hi:[0,1]
	s_nop 0
	v_cvt_pk_bf16_f32 v163, v172, v173
	v_lshlrev_b32_e32 v172, 16, v164
	v_and_b32_e32 v173, 0xffff0000, v164
	v_pk_add_f32 v[172:173], v[146:147], v[172:173] neg_lo:[0,1] neg_hi:[0,1]
	s_nop 0
	v_cvt_pk_bf16_f32 v164, v172, v173
	v_lshlrev_b32_e32 v172, 16, v165
	v_and_b32_e32 v173, 0xffff0000, v165
	v_pk_add_f32 v[172:173], v[148:149], v[172:173] neg_lo:[0,1] neg_hi:[0,1]
	s_nop 0
	v_cvt_pk_bf16_f32 v165, v172, v173
	flat_store_dwordx4 v[168:169], v[162:165] offset:256

; DI unsigned cvtpk(float lo, float hi) { f32x2_t v = {lo, hi}; bf16x2_t b = __builtin_convertvector(v, bf16x2_t); return __builtin_bit_cast(unsigned, b); }
; DI float bflo(unsigned w) { return __uint_as_float(w << 16); }
; DI float bfhi(unsigned w) { return __uint_as_float(w & 0xffff0000u); }
;     DI void operator()(const f32x4 (&acc)[2][2][4][2], const Unit& u, int wr, int wc, int fr, int fq) const {
;     ...
;                     if (loout) { u32x4 wl;
; #pragma unroll
;                         for (int j = 0; j < 4; ++j) wl[j] = cvtpk(o[2 * j] - bflo(w[j]), o[2 * j + 1] - bfhi(w[j]));
;                         __builtin_nontemporal_store(wl, (u32x4*)(loout + o2)); }
.LBB0_587:
	s_cmp_eq_u64 s[0:1], 0
	s_cbranch_scc1 .LBB0_589
	v_lshlrev_b32_e32 v154, 16, v146
	v_and_b32_e32 v155, 0xffff0000, v146
	v_pk_add_f32 v[154:155], v[142:143], v[154:155] neg_lo:[0,1] neg_hi:[0,1]
	s_nop 0
	v_cvt_pk_bf16_f32 v146, v154, v155
	v_lshlrev_b32_e32 v154, 16, v147
	v_and_b32_e32 v155, 0xffff0000, v147
	v_pk_add_f32 v[154:155], v[144:145], v[154:155] neg_lo:[0,1] neg_hi:[0,1]
	s_nop 0
	v_cvt_pk_bf16_f32 v147, v154, v155
	v_lshlrev_b32_e32 v154, 16, v148
	v_and_b32_e32 v155, 0xffff0000, v148
	v_pk_add_f32 v[154:155], v[138:139], v[154:155] neg_lo:[0,1] neg_hi:[0,1]
	s_nop 0
	v_cvt_pk_bf16_f32 v148, v154, v155
	v_lshlrev_b32_e32 v154, 16, v149
	v_and_b32_e32 v155, 0xffff0000, v149
	v_pk_add_f32 v[154:155], v[140:141], v[154:155] neg_lo:[0,1] neg_hi:[0,1]
	s_nop 0
	v_cvt_pk_bf16_f32 v149, v154, v155
	v_lshl_add_u64 v[154:155], v[152:153], 1, s[0:1]
	flat_store_dwordx4 v[154:155], v[146:149]

; DI unsigned cvtpk(float lo, float hi) { f32x2_t v = {lo, hi}; bf16x2_t b = __builtin_convertvector(v, bf16x2_t); return __builtin_bit_cast(unsigned, b); }
; DI float bflo(unsigned w) { return __uint_as_float(w << 16); }
; DI float bfhi(unsigned w) { return __uint_as_float(w & 0xffff0000u); }
;     DI void operator()(const f32x4 (&acc)[2][2][4][2], const Unit& u, int wr, int wc, int fr, int fq) const {
;     ...
;                     if (loout) { u32x4 wl;
; #pragma unroll
;                         for (int j = 0; j < 4; ++j) wl[j] = cvtpk(o[2 * j] - bflo(w[j]), o[2 * j + 1] - bfhi(w[j]));
;                         __builtin_nontemporal_store(wl, (u32x4*)(loout + o2)); }
.LBB0_595:
	s_cmp_eq_u64 s[0:1], 0
	s_cbranch_scc1 .LBB0_597
	v_lshlrev_b32_e32 v156, 16, v146
	v_and_b32_e32 v157, 0xffff0000, v146
	v_pk_add_f32 v[156:157], v[134:135], v[156:157] neg_lo:[0,1] neg_hi:[0,1]
	v_lshl_add_u64 v[152:153], v[152:153], 1, s[0:1]
	v_cvt_pk_bf16_f32 v146, v156, v157
	v_lshlrev_b32_e32 v156, 16, v147
	v_and_b32_e32 v157, 0xffff0000, v147
	v_pk_add_f32 v[156:157], v[136:137], v[156:157] neg_lo:[0,1] neg_hi:[0,1]
	s_nop 0
	v_cvt_pk_bf16_f32 v147, v156, v157
	v_lshlrev_b32_e32 v156, 16, v148
	v_and_b32_e32 v157, 0xffff0000, v148
	v_pk_add_f32 v[156:157], v[130:131], v[156:157] neg_lo:[0,1] neg_hi:[0,1]
	s_nop 0
	v_cvt_pk_bf16_f32 v148, v156, v157
	v_lshlrev_b32_e32 v156, 16, v149
	v_and_b32_e32 v157, 0xffff0000, v149
	v_pk_add_f32 v[156:157], v[132:133], v[156:157] neg_lo:[0,1] neg_hi:[0,1]
	s_nop 0
	v_cvt_pk_bf16_f32 v149, v156, v157
	flat_store_dwordx4 v[152:153], v[146:149] offset:256

; DI unsigned cvtpk(float lo, float hi) { f32x2_t v = {lo, hi}; bf16x2_t b = __builtin_convertvector(v, bf16x2_t); return __builtin_bit_cast(unsigned, b); }
; DI float bflo(unsigned w) { return __uint_as_float(w << 16); }
; DI float bfhi(unsigned w) { return __uint_as_float(w & 0xffff0000u); }
;     DI void operator()(const f32x4 (&acc)[2][2][4][2], const Unit& u, int wr, int wc, int fr, int fq) const {
;     ...
;                     if (loout) { u32x4 wl;
; #pragma unroll
;                         for (int j = 0; j < 4; ++j) wl[j] = cvtpk(o[2 * j] - bflo(w[j]), o[2 * j + 1] - bfhi(w[j]));
;                         __builtin_nontemporal_store(wl, (u32x4*)(loout + o2)); }
.LBB0_607:
	s_cmp_eq_u64 s[0:1], 0
	s_cbranch_scc1 .LBB0_609
	v_lshlrev_b32_e32 v206, 16, v194
	v_and_b32_e32 v207, 0xffff0000, v194
	v_pk_add_f32 v[206:207], v[186:187], v[206:207] neg_lo:[0,1] neg_hi:[0,1]
	s_nop 0
	v_cvt_pk_bf16_f32 v194, v206, v207
	v_lshlrev_b32_e32 v206, 16, v195
	v_and_b32_e32 v207, 0xffff0000, v195
	v_pk_add_f32 v[206:207], v[188:189], v[206:207] neg_lo:[0,1] neg_hi:[0,1]
	s_nop 0
	v_cvt_pk_bf16_f32 v195, v206, v207
	v_lshlrev_b32_e32 v206, 16, v196
	v_and_b32_e32 v207, 0xffff0000, v196
	v_pk_add_f32 v[206:207], v[190:191], v[206:207] neg_lo:[0,1] neg_hi:[0,1]
	s_nop 0
	v_cvt_pk_bf16_f32 v196, v206, v207
	v_lshlrev_b32_e32 v206, 16, v197
	v_and_b32_e32 v207, 0xffff0000, v197
	v_pk_add_f32 v[206:207], v[192:193], v[206:207] neg_lo:[0,1] neg_hi:[0,1]
	s_nop 0
	v_cvt_pk_bf16_f32 v197, v206, v207
	v_lshl_add_u64 v[206:207], v[222:223], 1, s[0:1]
	flat_store_dwordx4 v[206:207], v[194:197]

; DI unsigned cvtpk(float lo, float hi) { f32x2_t v = {lo, hi}; bf16x2_t b = __builtin_convertvector(v, bf16x2_t); return __builtin_bit_cast(unsigned, b); }
; DI float bflo(unsigned w) { return __uint_as_float(w << 16); }
; DI float bfhi(unsigned w) { return __uint_as_float(w & 0xffff0000u); }
;     DI void operator()(const f32x4 (&acc)[2][2][4][2], const Unit& u, int wr, int wc, int fr, int fq) const {
;     ...
;                     if (loout) { u32x4 wl;
; #pragma unroll
;                         for (int j = 0; j < 4; ++j) wl[j] = cvtpk(o[2 * j] - bflo(w[j]), o[2 * j + 1] - bfhi(w[j]));
;                         __builtin_nontemporal_store(wl, (u32x4*)(loout + o2)); }
.LBB0_615:
	s_cmp_eq_u64 s[0:1], 0
	s_cbranch_scc1 .LBB0_617
	v_lshlrev_b32_e32 v206, 16, v194
	v_and_b32_e32 v207, 0xffff0000, v194
	v_pk_add_f32 v[206:207], v[182:183], v[206:207] neg_lo:[0,1] neg_hi:[0,1]
	s_nop 0
	v_cvt_pk_bf16_f32 v194, v206, v207
	v_lshlrev_b32_e32 v206, 16, v195
	v_and_b32_e32 v207, 0xffff0000, v195
	v_pk_add_f32 v[206:207], v[184:185], v[206:207] neg_lo:[0,1] neg_hi:[0,1]
	s_nop 0
	v_cvt_pk_bf16_f32 v195, v206, v207
	v_lshlrev_b32_e32 v206, 16, v196
	v_and_b32_e32 v207, 0xffff0000, v196
	v_pk_add_f32 v[206:207], v[178:179], v[206:207] neg_lo:[0,1] neg_hi:[0,1]
	s_nop 0
	v_cvt_pk_bf16_f32 v196, v206, v207
	v_lshlrev_b32_e32 v206, 16, v197
	v_and_b32_e32 v207, 0xffff0000, v197
	v_pk_add_f32 v[206:207], v[180:181], v[206:207] neg_lo:[0,1] neg_hi:[0,1]
	s_nop 0
	v_cvt_pk_bf16_f32 v197, v206, v207
	v_lshl_add_u64 v[206:207], v[222:223], 1, s[0:1]
	flat_store_dwordx4 v[206:207], v[194:197] offset:256
